# v21thrfold
# speedup vs baseline: 1.0053x; 1.0029x over previous
; #define SBAR() __builtin_amdgcn_sched_barrier(0)
; #define PV_RD(F_, d0) do { constexpr int b_ = V_OFF + v_rd_off(d0, 0, 0); \
;         TRRD(F_[0], b_); TRRD(F_[1], b_ + 2048); TRRD(F_[2], b_ + 4096); TRRD(F_[3], b_ + 6144); TRRD(F_[4], b_ + 8192); TRRD(F_[5], b_ + 10240); TRRD(F_[6], b_ + 12288); TRRD(F_[7], b_ + 14336); } while (0)
; template <int k> __device__ __forceinline__ void par_snip(f32x16& p0, f32x16& p1, float& m_reg, float& pmax, float& alpha, float& mnL, float msk) {
;     constexpr float C2 = 1.4426950408889634f * SCALE;
;     if constexpr (k < 4) { constexpr int j = 4 * k; const float a = fmaxf(fmaxf(p0[j], p0[j + 1]), fmaxf(p0[j + 2], p0[j + 3])), b = fmaxf(fmaxf(p1[j], p1[j + 1]), fmaxf(p1[j + 2], p1[j + 3]));
;         pmax = (k == 0) ? fmaxf(a, b) : fmaxf(pmax, fmaxf(a, b)); }
;     else if constexpr (k == 4) { pmax += msk;
;         { auto rr = __builtin_amdgcn_permlane32_swap(__float_as_uint(pmax), __float_as_uint(pmax), false, false); pmax = fmaxf(__uint_as_float(rr[0]), __uint_as_float(rr[1])); }
;         const bool defer = __all((pmax - m_reg) * SCALE <= THR);
;         const float mn = defer ? m_reg : fmaxf(m_reg, pmax);
;         alpha = __builtin_amdgcn_exp2f((m_reg - mn) * C2); m_reg = mn; mnL = fmaf(-mn, C2, msk); }
;     else if constexpr (k < 9) { constexpr int j = 4 * (k - 5);
; #pragma unroll
;         for (int e = 0; e < 4; ++e) { p0[j + e] = fmaf(p0[j + e], C2, mnL); p1[j + e] = fmaf(p1[j + e], C2, mnL); } }
;     else if constexpr (k < 15) { constexpr int j = 2 * (k - 9); p0[j] = __builtin_amdgcn_exp2f(p0[j]); p0[j + 1] = __builtin_amdgcn_exp2f(p0[j + 1]); }
;     else if constexpr (k == 15) {
; #pragma unroll
;         for (int e = 12; e < 16; ++e) p0[e] = __builtin_amdgcn_exp2f(p0[e]); }
; __device__ __forceinline__ void stage_pv_par(f32x16* o, int vb0, bf16x8 pa0, bf16x8 pa1, bf16x8 pa2, bf16x8 pa3,
;                                              f32x16& x0, f32x16& x1, float& m_reg, float& alpha, float msk) {
;     ...
;     float pmax = 0.f, mnL = 0.f; s16x4 fA[8];
;     SBAR(); PV_RD(fA, 0); PV_WAIT(fA, 0); SBAR();
;     PVS(fA, 0); PV_RD(fA, 1); PV_WAIT(fA, 0); SBAR();
;     PVS(fA, 1); PV_RD(fA, 2); PV_WAIT(fA, 0); SBAR();
;     PVS(fA, 2); PV_RD(fA, 3); PV_WAIT(fA, 0); SBAR();
;     PVS(fA, 3);
.Lmy_mid_a:
	s_and_b32 s34, s85, 0xc000
	v_add_u32_e32 v217, s34, v225
	ds_read_b64_tr_b16 v[194:195], v217 offset:0
	ds_read_b64_tr_b16 v[196:197], v217 offset:0x800
	ds_read_b64_tr_b16 v[200:201], v217 offset:0x1000
	ds_read_b64_tr_b16 v[202:203], v217 offset:0x1800
	ds_read_b64_tr_b16 v[204:205], v217 offset:0x2000
	ds_read_b64_tr_b16 v[206:207], v217 offset:0x2800
	ds_read_b64_tr_b16 v[208:209], v217 offset:0x3000
	ds_read_b64_tr_b16 v[210:211], v217 offset:0x3800
	s_nop 0
	s_waitcnt lgkmcnt(0)
	s_nop 0
	v_mfma_f32_32x32x16_bf16 v[64:79], v[194:197], v[2:5], v[64:79]
	s_nop 5
	v_max3_f32 v0, v96, v97, v98
	v_max3_f32 v194, v112, v113, v114
	v_max3_f32 v0, v0, v99, v100
	v_max3_f32 v194, v194, v115, v116
	v_mfma_f32_32x32x16_bf16 v[64:79], v[200:203], v[6:9], v[64:79]
	v_max3_f32 v0, v0, v101, v102
	v_max3_f32 v194, v194, v117, v118
	v_max3_f32 v0, v0, v103, v104
	v_max3_f32 v194, v194, v119, v120
	v_mfma_f32_32x32x16_bf16 v[64:79], v[204:207], v[10:13], v[64:79]
	v_max3_f32 v0, v0, v105, v106
	v_max3_f32 v194, v194, v121, v122
	v_max3_f32 v0, v0, v107, v108
	v_max3_f32 v194, v194, v123, v124
	v_mfma_f32_32x32x16_bf16 v[64:79], v[208:211], v[176:179], v[64:79]
	v_max3_f32 v0, v0, v109, v110
	v_max3_f32 v194, v194, v125, v126
	v_max3_f32 v0, v0, v111, v127
	v_max_f32_e32 v0, v0, v194
	ds_read_b64_tr_b16 v[194:195], v217 offset:0x200
	ds_read_b64_tr_b16 v[196:197], v217 offset:0xa00
	ds_read_b64_tr_b16 v[200:201], v217 offset:0x1200
	ds_read_b64_tr_b16 v[202:203], v217 offset:0x1a00
	ds_read_b64_tr_b16 v[204:205], v217 offset:0x2200
	ds_read_b64_tr_b16 v[206:207], v217 offset:0x2a00
	ds_read_b64_tr_b16 v[208:209], v217 offset:0x3200
	ds_read_b64_tr_b16 v[210:211], v217 offset:0x3a00
	s_nop 0
	s_waitcnt lgkmcnt(0)
	v_add_f32_e32 v0, v216, v0
	v_mfma_f32_32x32x16_bf16 v[48:63], v[194:197], v[2:5], v[48:63]
	v_mov_b32_e32 v194, v0
	s_nop 1
	v_permlane32_swap_b32_e32 v0, v194
	v_max_f32_e32 v0, v0, v194
	v_sub_f32_e32 v194, v0, v244
	v_cmp_ge_f32_e32 vcc, 0x42ddb3d8, v194
	v_max_f32_e32 v0, v244, v0
	s_nop 0
	v_cndmask_b32_e32 v246, v0, v244, vcc
	v_sub_f32_e32 v0, v244, v246
	v_mul_f32_e32 v0, 0x3dd53b94, v0
	v_exp_f32_e32 v0, v0
	v_fmac_f32_e32 v216, 0xbdd53b94, v246
	v_mfma_f32_32x32x16_bf16 v[48:63], v[200:203], v[6:9], v[48:63]
	v_fmamk_f32 v96, v96, 0x3dd53b94, v216
	v_fmamk_f32 v97, v97, 0x3dd53b94, v216
	v_fmamk_f32 v98, v98, 0x3dd53b94, v216
	v_fmamk_f32 v99, v99, 0x3dd53b94, v216
	v_exp_f32_e32 v243, v96
	v_mfma_f32_32x32x16_bf16 v[48:63], v[204:207], v[10:13], v[48:63]
	v_fmamk_f32 v100, v100, 0x3dd53b94, v216
	v_fmamk_f32 v101, v101, 0x3dd53b94, v216
	v_exp_f32_e32 v242, v97
	v_exp_f32_e32 v241, v98
	v_mfma_f32_32x32x16_bf16 v[48:63], v[208:211], v[176:179], v[48:63]
	v_fmamk_f32 v102, v102, 0x3dd53b94, v216
	v_fmamk_f32 v103, v103, 0x3dd53b94, v216
	v_exp_f32_e32 v240, v99
	v_exp_f32_e32 v239, v100
	ds_read_b64_tr_b16 v[194:195], v217 offset:0x400
	ds_read_b64_tr_b16 v[196:197], v217 offset:0xc00
	ds_read_b64_tr_b16 v[200:201], v217 offset:0x1400
	ds_read_b64_tr_b16 v[202:203], v217 offset:0x1c00
	ds_read_b64_tr_b16 v[204:205], v217 offset:0x2400
	ds_read_b64_tr_b16 v[206:207], v217 offset:0x2c00
	ds_read_b64_tr_b16 v[208:209], v217 offset:0x3400
	ds_read_b64_tr_b16 v[210:211], v217 offset:0x3c00
	s_nop 0
	s_waitcnt lgkmcnt(0)
	s_nop 0
	v_mfma_f32_32x32x16_bf16 v[32:47], v[194:197], v[2:5], v[32:47]
	v_fmamk_f32 v104, v104, 0x3dd53b94, v216
	v_fmamk_f32 v105, v105, 0x3dd53b94, v216
	v_exp_f32_e32 v238, v101
	v_exp_f32_e32 v237, v102
	v_mfma_f32_32x32x16_bf16 v[32:47], v[200:203], v[6:9], v[32:47]
	v_fmamk_f32 v106, v106, 0x3dd53b94, v216
	v_fmamk_f32 v107, v107, 0x3dd53b94, v216
	v_exp_f32_e32 v236, v103
	v_exp_f32_e32 v235, v104
	v_mfma_f32_32x32x16_bf16 v[32:47], v[204:207], v[10:13], v[32:47]
	v_fmamk_f32 v108, v108, 0x3dd53b94, v216
	v_fmamk_f32 v109, v109, 0x3dd53b94, v216
	v_exp_f32_e32 v234, v105
	v_exp_f32_e32 v233, v106
	v_mfma_f32_32x32x16_bf16 v[32:47], v[208:211], v[176:179], v[32:47]
	v_fmamk_f32 v110, v110, 0x3dd53b94, v216
	v_fmamk_f32 v111, v111, 0x3dd53b94, v216
	v_exp_f32_e32 v232, v107
	v_exp_f32_e32 v231, v108
	ds_read_b64_tr_b16 v[194:195], v217 offset:0x600
	ds_read_b64_tr_b16 v[196:197], v217 offset:0xe00
	ds_read_b64_tr_b16 v[200:201], v217 offset:0x1600
	ds_read_b64_tr_b16 v[202:203], v217 offset:0x1e00
	ds_read_b64_tr_b16 v[204:205], v217 offset:0x2600
	ds_read_b64_tr_b16 v[206:207], v217 offset:0x2e00
	ds_read_b64_tr_b16 v[208:209], v217 offset:0x3600
	ds_read_b64_tr_b16 v[210:211], v217 offset:0x3e00
	s_nop 0
	s_waitcnt lgkmcnt(0)
	s_nop 0
	v_mfma_f32_32x32x16_bf16 v[16:31], v[194:197], v[2:5], v[16:31]
	v_exp_f32_e32 v230, v109
	v_fmamk_f32 v14, v112, 0x3dd53b94, v216
	v_fmamk_f32 v15, v113, 0x3dd53b94, v216
	v_fmamk_f32 v116, v116, 0x3dd53b94, v216
	v_fmamk_f32 v117, v117, 0x3dd53b94, v216
	v_mfma_f32_32x32x16_bf16 v[16:31], v[200:203], v[6:9], v[16:31]
	v_fmamk_f32 v118, v118, 0x3dd53b94, v216
	v_fmamk_f32 v119, v119, 0x3dd53b94, v216
	v_fmamk_f32 v120, v120, 0x3dd53b94, v216
	v_fmamk_f32 v121, v121, 0x3dd53b94, v216
	v_fmamk_f32 v122, v122, 0x3dd53b94, v216
	v_fmamk_f32 v123, v123, 0x3dd53b94, v216
	v_mfma_f32_32x32x16_bf16 v[16:31], v[204:207], v[10:13], v[16:31]
	v_fmamk_f32 v124, v124, 0x3dd53b94, v216
	v_fmamk_f32 v125, v125, 0x3dd53b94, v216
	v_fmamk_f32 v126, v126, 0x3dd53b94, v216
	v_fmamk_f32 v127, v127, 0x3dd53b94, v216
	v_mfma_f32_32x32x16_bf16 v[16:31], v[208:211], v[176:179], v[16:31]
	v_cmp_gt_f32_e32 vcc, 1.0, v0
	s_cbranch_vccz .LBB0_330
	v_pk_mul_f32 v[78:79], v[78:79], v[0:1] op_sel_hi:[1,0]
	v_pk_mul_f32 v[76:77], v[76:77], v[0:1] op_sel_hi:[1,0]
	v_pk_mul_f32 v[74:75], v[74:75], v[0:1] op_sel_hi:[1,0]
	v_pk_mul_f32 v[72:73], v[72:73], v[0:1] op_sel_hi:[1,0]
	v_pk_mul_f32 v[70:71], v[70:71], v[0:1] op_sel_hi:[1,0]
	v_pk_mul_f32 v[68:69], v[68:69], v[0:1] op_sel_hi:[1,0]
	v_pk_mul_f32 v[66:67], v[66:67], v[0:1] op_sel_hi:[1,0]
	v_pk_mul_f32 v[64:65], v[64:65], v[0:1] op_sel_hi:[1,0]
	v_pk_mul_f32 v[62:63], v[0:1], v[62:63] op_sel_hi:[0,1]
	v_pk_mul_f32 v[60:61], v[0:1], v[60:61] op_sel_hi:[0,1]
	v_pk_mul_f32 v[58:59], v[0:1], v[58:59] op_sel_hi:[0,1]
	v_pk_mul_f32 v[56:57], v[0:1], v[56:57] op_sel_hi:[0,1]
	v_pk_mul_f32 v[54:55], v[0:1], v[54:55] op_sel_hi:[0,1]
	v_pk_mul_f32 v[52:53], v[0:1], v[52:53] op_sel_hi:[0,1]
	v_pk_mul_f32 v[50:51], v[0:1], v[50:51] op_sel_hi:[0,1]
	v_pk_mul_f32 v[48:49], v[0:1], v[48:49] op_sel_hi:[0,1]
	v_pk_mul_f32 v[46:47], v[0:1], v[46:47] op_sel_hi:[0,1]
	v_pk_mul_f32 v[44:45], v[0:1], v[44:45] op_sel_hi:[0,1]
	v_pk_mul_f32 v[42:43], v[0:1], v[42:43] op_sel_hi:[0,1]
	v_pk_mul_f32 v[40:41], v[0:1], v[40:41] op_sel_hi:[0,1]
	v_pk_mul_f32 v[38:39], v[0:1], v[38:39] op_sel_hi:[0,1]
	v_pk_mul_f32 v[36:37], v[0:1], v[36:37] op_sel_hi:[0,1]
	v_pk_mul_f32 v[34:35], v[0:1], v[34:35] op_sel_hi:[0,1]
	v_pk_mul_f32 v[32:33], v[0:1], v[32:33] op_sel_hi:[0,1]
	v_pk_mul_f32 v[30:31], v[0:1], v[30:31] op_sel_hi:[0,1]
	v_pk_mul_f32 v[28:29], v[0:1], v[28:29] op_sel_hi:[0,1]
	v_pk_mul_f32 v[26:27], v[0:1], v[26:27] op_sel_hi:[0,1]
	v_pk_mul_f32 v[24:25], v[0:1], v[24:25] op_sel_hi:[0,1]
	v_pk_mul_f32 v[22:23], v[0:1], v[22:23] op_sel_hi:[0,1]
	v_pk_mul_f32 v[20:21], v[0:1], v[20:21] op_sel_hi:[0,1]
	v_pk_mul_f32 v[18:19], v[0:1], v[18:19] op_sel_hi:[0,1]
	v_pk_mul_f32 v[16:17], v[0:1], v[16:17] op_sel_hi:[0,1]

; #define SBAR() __builtin_amdgcn_sched_barrier(0)
; #define PV_RD(F_, d0) do { constexpr int b_ = V_OFF + v_rd_off(d0, 0, 0); \
;         TRRD(F_[0], b_); TRRD(F_[1], b_ + 2048); TRRD(F_[2], b_ + 4096); TRRD(F_[3], b_ + 6144); TRRD(F_[4], b_ + 8192); TRRD(F_[5], b_ + 10240); TRRD(F_[6], b_ + 12288); TRRD(F_[7], b_ + 14336); } while (0)
; template <int k> __device__ __forceinline__ void par_snip(f32x16& p0, f32x16& p1, float& m_reg, float& pmax, float& alpha, float& mnL, float msk) {
;     constexpr float C2 = 1.4426950408889634f * SCALE;
;     if constexpr (k < 4) { constexpr int j = 4 * k; const float a = fmaxf(fmaxf(p0[j], p0[j + 1]), fmaxf(p0[j + 2], p0[j + 3])), b = fmaxf(fmaxf(p1[j], p1[j + 1]), fmaxf(p1[j + 2], p1[j + 3]));
;         pmax = (k == 0) ? fmaxf(a, b) : fmaxf(pmax, fmaxf(a, b)); }
;     else if constexpr (k == 4) { pmax += msk;
;         { auto rr = __builtin_amdgcn_permlane32_swap(__float_as_uint(pmax), __float_as_uint(pmax), false, false); pmax = fmaxf(__uint_as_float(rr[0]), __uint_as_float(rr[1])); }
;         const bool defer = __all((pmax - m_reg) * SCALE <= THR);
;         const float mn = defer ? m_reg : fmaxf(m_reg, pmax);
;         alpha = __builtin_amdgcn_exp2f((m_reg - mn) * C2); m_reg = mn; mnL = fmaf(-mn, C2, msk); }
;     else if constexpr (k < 9) { constexpr int j = 4 * (k - 5);
; #pragma unroll
;         for (int e = 0; e < 4; ++e) { p0[j + e] = fmaf(p0[j + e], C2, mnL); p1[j + e] = fmaf(p1[j + e], C2, mnL); } }
;     else if constexpr (k < 15) { constexpr int j = 2 * (k - 9); p0[j] = __builtin_amdgcn_exp2f(p0[j]); p0[j + 1] = __builtin_amdgcn_exp2f(p0[j + 1]); }
;     else if constexpr (k == 15) {
; #pragma unroll
;         for (int e = 12; e < 16; ++e) p0[e] = __builtin_amdgcn_exp2f(p0[e]); }
; __device__ __forceinline__ void stage_pv_par(f32x16* o, int vb0, bf16x8 pa0, bf16x8 pa1, bf16x8 pa2, bf16x8 pa3,
;                                              f32x16& x0, f32x16& x1, float& m_reg, float& alpha, float msk) {
;     ...
;     float pmax = 0.f, mnL = 0.f; s16x4 fA[8];
;     SBAR(); PV_RD(fA, 0); PV_WAIT(fA, 0); SBAR();
;     PVS(fA, 0); PV_RD(fA, 1); PV_WAIT(fA, 0); SBAR();
;     PVS(fA, 1); PV_RD(fA, 2); PV_WAIT(fA, 0); SBAR();
;     PVS(fA, 2); PV_RD(fA, 3); PV_WAIT(fA, 0); SBAR();
;     PVS(fA, 3);
.Lmy_mid_b:
	s_and_b32 s34, s34, 0xc000
	v_add_u32_e32 v217, s34, v225
	ds_read_b64_tr_b16 v[194:195], v217 offset:0
	ds_read_b64_tr_b16 v[196:197], v217 offset:0x800
	ds_read_b64_tr_b16 v[232:233], v217 offset:0x1000
	ds_read_b64_tr_b16 v[234:235], v217 offset:0x1800
	ds_read_b64_tr_b16 v[236:237], v217 offset:0x2000
	ds_read_b64_tr_b16 v[238:239], v217 offset:0x2800
	ds_read_b64_tr_b16 v[240:241], v217 offset:0x3000
	ds_read_b64_tr_b16 v[242:243], v217 offset:0x3800
	s_nop 0
	s_waitcnt lgkmcnt(0)
	s_nop 0
	v_mfma_f32_32x32x16_bf16 v[64:79], v[194:197], v[2:5], v[64:79]
	s_nop 5
	v_max3_f32 v192, v96, v97, v98
	v_max3_f32 v194, v80, v81, v82
	v_max3_f32 v192, v192, v99, v100
	v_max3_f32 v194, v194, v83, v84
	v_mfma_f32_32x32x16_bf16 v[64:79], v[232:235], v[6:9], v[64:79]
	v_max3_f32 v192, v192, v101, v102
	v_max3_f32 v194, v194, v85, v86
	v_max3_f32 v192, v192, v103, v104
	v_max3_f32 v194, v194, v87, v88
	v_mfma_f32_32x32x16_bf16 v[64:79], v[236:239], v[10:13], v[64:79]
	v_max3_f32 v192, v192, v105, v106
	v_max3_f32 v194, v194, v89, v90
	v_max3_f32 v192, v192, v107, v108
	v_max3_f32 v194, v194, v91, v92
	v_mfma_f32_32x32x16_bf16 v[64:79], v[240:243], v[112:115], v[64:79]
	v_max3_f32 v192, v192, v109, v110
	v_max3_f32 v194, v194, v93, v94
	v_max3_f32 v192, v192, v111, v95
	v_max_f32_e32 v192, v192, v194
	ds_read_b64_tr_b16 v[194:195], v217 offset:0x200
	ds_read_b64_tr_b16 v[196:197], v217 offset:0xa00
	ds_read_b64_tr_b16 v[232:233], v217 offset:0x1200
	ds_read_b64_tr_b16 v[234:235], v217 offset:0x1a00
	ds_read_b64_tr_b16 v[236:237], v217 offset:0x2200
	ds_read_b64_tr_b16 v[238:239], v217 offset:0x2a00
	ds_read_b64_tr_b16 v[240:241], v217 offset:0x3200
	ds_read_b64_tr_b16 v[242:243], v217 offset:0x3a00
	s_nop 0
	s_waitcnt lgkmcnt(0)
	v_add_f32_e32 v192, v178, v192
	v_mfma_f32_32x32x16_bf16 v[48:63], v[194:197], v[2:5], v[48:63]
	v_mov_b32_e32 v194, v192
	s_nop 1
	v_permlane32_swap_b32_e32 v192, v194
	v_max_f32_e32 v192, v192, v194
	v_sub_f32_e32 v194, v192, v246
	v_cmp_ge_f32_e32 vcc, 0x42ddb3d8, v194
	v_max_f32_e32 v192, v246, v192
	s_nop 0
	v_cndmask_b32_e32 v244, v192, v246, vcc
	v_sub_f32_e32 v192, v246, v244
	v_mul_f32_e32 v192, 0x3dd53b94, v192
	v_exp_f32_e32 v192, v192
	v_fmac_f32_e32 v178, 0xbdd53b94, v244
	v_mfma_f32_32x32x16_bf16 v[48:63], v[232:235], v[6:9], v[48:63]
	v_fmamk_f32 v214, v80, 0x3dd53b94, v178
	v_fmamk_f32 v215, v81, 0x3dd53b94, v178
	v_fmamk_f32 v212, v82, 0x3dd53b94, v178
	v_fmamk_f32 v213, v83, 0x3dd53b94, v178
	v_fmamk_f32 v210, v84, 0x3dd53b94, v178
	v_fmamk_f32 v211, v85, 0x3dd53b94, v178
	v_mfma_f32_32x32x16_bf16 v[48:63], v[236:239], v[10:13], v[48:63]
	v_fmamk_f32 v208, v86, 0x3dd53b94, v178
	v_fmamk_f32 v209, v87, 0x3dd53b94, v178
	v_fmamk_f32 v206, v88, 0x3dd53b94, v178
	v_fmamk_f32 v207, v89, 0x3dd53b94, v178
	v_fmamk_f32 v204, v90, 0x3dd53b94, v178
	v_fmamk_f32 v205, v91, 0x3dd53b94, v178
	v_mfma_f32_32x32x16_bf16 v[48:63], v[240:243], v[112:115], v[48:63]
	v_fmamk_f32 v202, v92, 0x3dd53b94, v178
	v_fmamk_f32 v203, v93, 0x3dd53b94, v178
	v_fmamk_f32 v200, v94, 0x3dd53b94, v178
	v_fmamk_f32 v201, v95, 0x3dd53b94, v178
	v_fmamk_f32 v96, v96, 0x3dd53b94, v178
	v_fmamk_f32 v97, v97, 0x3dd53b94, v178
	ds_read_b64_tr_b16 v[194:195], v217 offset:0x400
	ds_read_b64_tr_b16 v[196:197], v217 offset:0xc00
	ds_read_b64_tr_b16 v[232:233], v217 offset:0x1400
	ds_read_b64_tr_b16 v[234:235], v217 offset:0x1c00
	ds_read_b64_tr_b16 v[236:237], v217 offset:0x2400
	ds_read_b64_tr_b16 v[238:239], v217 offset:0x2c00
	ds_read_b64_tr_b16 v[240:241], v217 offset:0x3400
	ds_read_b64_tr_b16 v[242:243], v217 offset:0x3c00
	s_nop 0
	s_waitcnt lgkmcnt(0)
	s_nop 0
	v_mfma_f32_32x32x16_bf16 v[32:47], v[194:197], v[2:5], v[32:47]
	v_fmamk_f32 v98, v98, 0x3dd53b94, v178
	v_fmamk_f32 v99, v99, 0x3dd53b94, v178
	v_exp_f32_e32 v80, v96
	v_exp_f32_e32 v81, v97
	v_mfma_f32_32x32x16_bf16 v[32:47], v[232:235], v[6:9], v[32:47]
	v_fmamk_f32 v100, v100, 0x3dd53b94, v178
	v_fmamk_f32 v101, v101, 0x3dd53b94, v178
	v_exp_f32_e32 v82, v98
	v_exp_f32_e32 v83, v99
	v_mfma_f32_32x32x16_bf16 v[32:47], v[236:239], v[10:13], v[32:47]
	v_fmamk_f32 v102, v102, 0x3dd53b94, v178
	v_fmamk_f32 v103, v103, 0x3dd53b94, v178
	v_exp_f32_e32 v84, v100
	v_exp_f32_e32 v85, v101
	v_mfma_f32_32x32x16_bf16 v[32:47], v[240:243], v[112:115], v[32:47]
	v_fmamk_f32 v104, v104, 0x3dd53b94, v178
	v_fmamk_f32 v105, v105, 0x3dd53b94, v178
	v_exp_f32_e32 v86, v102
	v_exp_f32_e32 v87, v103
	ds_read_b64_tr_b16 v[194:195], v217 offset:0x600
	ds_read_b64_tr_b16 v[196:197], v217 offset:0xe00
	ds_read_b64_tr_b16 v[232:233], v217 offset:0x1600
	ds_read_b64_tr_b16 v[234:235], v217 offset:0x1e00
	ds_read_b64_tr_b16 v[236:237], v217 offset:0x2600
	ds_read_b64_tr_b16 v[238:239], v217 offset:0x2e00
	ds_read_b64_tr_b16 v[240:241], v217 offset:0x3600
	ds_read_b64_tr_b16 v[242:243], v217 offset:0x3e00
	s_nop 0
	s_waitcnt lgkmcnt(0)
	s_nop 0
	v_mfma_f32_32x32x16_bf16 v[16:31], v[194:197], v[2:5], v[16:31]
	v_fmamk_f32 v106, v106, 0x3dd53b94, v178
	v_fmamk_f32 v107, v107, 0x3dd53b94, v178
	v_exp_f32_e32 v88, v104
	v_exp_f32_e32 v89, v105
	v_mfma_f32_32x32x16_bf16 v[16:31], v[232:235], v[6:9], v[16:31]
	v_fmamk_f32 v108, v108, 0x3dd53b94, v178
	v_fmamk_f32 v109, v109, 0x3dd53b94, v178
	v_exp_f32_e32 v90, v106
	v_exp_f32_e32 v91, v107
	v_mfma_f32_32x32x16_bf16 v[16:31], v[236:239], v[10:13], v[16:31]
	v_fmamk_f32 v110, v110, 0x3dd53b94, v178
	v_fmamk_f32 v111, v111, 0x3dd53b94, v178
	v_exp_f32_e32 v92, v108
	v_exp_f32_e32 v93, v109
	v_mfma_f32_32x32x16_bf16 v[16:31], v[240:243], v[112:115], v[16:31]
	v_cmp_gt_f32_e32 vcc, 1.0, v192
	s_cbranch_vccz .LBB0_335
	v_pk_mul_f32 v[78:79], v[78:79], v[192:193] op_sel_hi:[1,0]
	v_pk_mul_f32 v[76:77], v[76:77], v[192:193] op_sel_hi:[1,0]
	v_pk_mul_f32 v[74:75], v[74:75], v[192:193] op_sel_hi:[1,0]
	v_pk_mul_f32 v[72:73], v[72:73], v[192:193] op_sel_hi:[1,0]
	v_pk_mul_f32 v[70:71], v[70:71], v[192:193] op_sel_hi:[1,0]
	v_pk_mul_f32 v[68:69], v[68:69], v[192:193] op_sel_hi:[1,0]
	v_pk_mul_f32 v[66:67], v[66:67], v[192:193] op_sel_hi:[1,0]
	v_pk_mul_f32 v[64:65], v[64:65], v[192:193] op_sel_hi:[1,0]
	v_pk_mul_f32 v[62:63], v[192:193], v[62:63] op_sel_hi:[0,1]
	v_pk_mul_f32 v[60:61], v[192:193], v[60:61] op_sel_hi:[0,1]
	v_pk_mul_f32 v[58:59], v[192:193], v[58:59] op_sel_hi:[0,1]
	v_pk_mul_f32 v[56:57], v[192:193], v[56:57] op_sel_hi:[0,1]
	v_pk_mul_f32 v[54:55], v[192:193], v[54:55] op_sel_hi:[0,1]
	v_pk_mul_f32 v[52:53], v[192:193], v[52:53] op_sel_hi:[0,1]
	v_pk_mul_f32 v[50:51], v[192:193], v[50:51] op_sel_hi:[0,1]
	v_pk_mul_f32 v[48:49], v[192:193], v[48:49] op_sel_hi:[0,1]
	v_pk_mul_f32 v[46:47], v[192:193], v[46:47] op_sel_hi:[0,1]
	v_pk_mul_f32 v[44:45], v[192:193], v[44:45] op_sel_hi:[0,1]
	v_pk_mul_f32 v[42:43], v[192:193], v[42:43] op_sel_hi:[0,1]
	v_pk_mul_f32 v[40:41], v[192:193], v[40:41] op_sel_hi:[0,1]
	v_pk_mul_f32 v[38:39], v[192:193], v[38:39] op_sel_hi:[0,1]
	v_pk_mul_f32 v[36:37], v[192:193], v[36:37] op_sel_hi:[0,1]
	v_pk_mul_f32 v[34:35], v[192:193], v[34:35] op_sel_hi:[0,1]
	v_pk_mul_f32 v[32:33], v[192:193], v[32:33] op_sel_hi:[0,1]
	v_pk_mul_f32 v[30:31], v[192:193], v[30:31] op_sel_hi:[0,1]
	v_pk_mul_f32 v[28:29], v[192:193], v[28:29] op_sel_hi:[0,1]
	v_pk_mul_f32 v[26:27], v[192:193], v[26:27] op_sel_hi:[0,1]
	v_pk_mul_f32 v[24:25], v[192:193], v[24:25] op_sel_hi:[0,1]
	v_pk_mul_f32 v[22:23], v[192:193], v[22:23] op_sel_hi:[0,1]
	v_pk_mul_f32 v[20:21], v[192:193], v[20:21] op_sel_hi:[0,1]
	v_pk_mul_f32 v[18:19], v[192:193], v[18:19] op_sel_hi:[0,1]
	v_pk_mul_f32 v[16:17], v[192:193], v[16:17] op_sel_hi:[0,1]
